# P8 deferred stores: per-iteration store entry selected at the loop back-edge (linear not-taken chain) instead of a branch tree at loop top
# speedup vs baseline: 1.0034x; 1.0034x over previous
.LBB0_876:
	s_ashr_i32 s27, s26, 31
	s_lshl_b64 s[28:29], s[26:27], 19
	s_add_u32 s28, s66, s28
	s_addc_u32 s29, s67, s29
	s_and_b64 s[30:31], s[4:5], exec
	s_cselect_b32 s27, s29, s37
	s_cselect_b32 s57, s28, s36
	s_ashr_i32 s25, s24, 31
	s_lshl_b64 s[30:31], s[24:25], 19
	s_add_u32 s30, s72, s30
	s_addc_u32 s31, s73, s31
	s_and_b64 s[40:41], s[4:5], exec
	s_cselect_b32 s25, s31, s39
	s_cselect_b32 s58, s30, s38
	s_add_u32 s36, s36, 0x40080
	s_addc_u32 s37, s37, 0
	s_add_u32 s59, s38, 0x100
	s_addc_u32 s60, s39, 0
	s_mov_b32 s61, -2
	v_mov_b64_e32 v[0:1], 0
	v_mov_b64_e32 v[2:3], 0
	v_mov_b64_e32 v[4:5], 0
	v_mov_b64_e32 v[6:7], 0
	v_mov_b64_e32 v[8:9], 0
	v_mov_b64_e32 v[10:11], 0
	v_mov_b64_e32 v[12:13], 0
	v_mov_b64_e32 v[14:15], 0
	v_mov_b64_e32 v[16:17], 0
	v_mov_b64_e32 v[18:19], 0
	v_mov_b64_e32 v[20:21], 0
	v_mov_b64_e32 v[22:23], 0
	v_mov_b64_e32 v[24:25], 0
	v_mov_b64_e32 v[26:27], 0
	v_mov_b64_e32 v[28:29], 0
	v_mov_b64_e32 v[30:31], 0
	v_mov_b64_e32 v[32:33], 0
	v_mov_b64_e32 v[34:35], 0
	v_mov_b64_e32 v[36:37], 0
	v_mov_b64_e32 v[38:39], 0
	v_mov_b64_e32 v[40:41], 0
	v_mov_b64_e32 v[42:43], 0
	v_mov_b64_e32 v[44:45], 0
	v_mov_b64_e32 v[46:47], 0
	v_mov_b64_e32 v[48:49], 0
	v_mov_b64_e32 v[50:51], 0
	v_mov_b64_e32 v[52:53], 0
	v_mov_b64_e32 v[54:55], 0
	v_mov_b64_e32 v[56:57], 0
	v_mov_b64_e32 v[58:59], 0
	v_mov_b64_e32 v[60:61], 0
	v_mov_b64_e32 v[62:63], 0
	v_mov_b64_e32 v[64:65], 0
	v_mov_b64_e32 v[66:67], 0
	v_mov_b64_e32 v[68:69], 0
	v_mov_b64_e32 v[70:71], 0
	v_mov_b64_e32 v[72:73], 0
	v_mov_b64_e32 v[74:75], 0
	v_mov_b64_e32 v[76:77], 0
	v_mov_b64_e32 v[78:79], 0
	v_mov_b64_e32 v[80:81], 0
	v_mov_b64_e32 v[82:83], 0
	v_mov_b64_e32 v[84:85], 0
	v_mov_b64_e32 v[86:87], 0
	v_mov_b64_e32 v[88:89], 0
	v_mov_b64_e32 v[90:91], 0
	v_mov_b64_e32 v[92:93], 0
	v_mov_b64_e32 v[94:95], 0
	v_mov_b64_e32 v[96:97], 0
	v_mov_b64_e32 v[98:99], 0
	v_mov_b64_e32 v[100:101], 0
	v_mov_b64_e32 v[102:103], 0
	v_mov_b64_e32 v[104:105], 0
	v_mov_b64_e32 v[106:107], 0
	v_mov_b64_e32 v[108:109], 0
	v_mov_b64_e32 v[110:111], 0
	v_mov_b64_e32 v[112:113], 0
	v_mov_b64_e32 v[114:115], 0
	v_mov_b64_e32 v[116:117], 0
	v_mov_b64_e32 v[118:119], 0
	v_mov_b64_e32 v[120:121], 0
	v_mov_b64_e32 v[122:123], 0
	v_mov_b64_e32 v[124:125], 0
	v_mov_b64_e32 v[126:127], 0
	s_cmp_eq_u32 s100, 0
	s_cbranch_scc1 .Ldhs8_idle0
	global_store_dwordx4 v255, v[226:229], s[16:17]
	s_branch .Ldhs8_body

.Ldhs8_e2:
	global_store_dwordx4 v255, v[234:237], s[16:17] offset:1024
	s_branch .Ldhs8_body

.Ldhs8_e4:
	global_store_dwordx4 v255, v[242:245], s[16:17] offset:2048
	s_branch .Ldhs8_body

.Ldhs8_e6:
	global_store_dwordx4 v255, v[250:253], s[16:17] offset:3072
	s_branch .Ldhs8_body
.Ldhs8_e7:
	global_store_dwordx4 v255, v[140:143], s[18:19] offset:3072
.Ldhs8_body:
.LBB0_877:
	ds_read_b128 v[150:153], v147
	ds_read_b128 v[154:157], v147 offset:1024
	ds_read_b128 v[158:161], v147 offset:2048
	ds_read_b128 v[162:165], v147 offset:3072
	ds_read_b128 v[166:169], v148
	ds_read_b128 v[170:173], v148 offset:1024
	ds_read_b128 v[174:177], v148 offset:2048
	ds_read_b128 v[178:181], v148 offset:3072
	s_add_u32 s38, s36, 0xfffc0080
	s_addc_u32 s39, s37, -1
	s_cmp_eq_u32 s61, 12
	s_cselect_b32 s41, s27, s39
	s_cselect_b32 s40, s57, s38
	s_cselect_b32 s39, s25, s60
	s_cselect_b32 s38, s58, s59
	v_lshl_add_u64 v[214:215], s[36:37], 0, v[136:137]
	s_add_i32 m0, s35, 0xc000
	ds_read_b128 v[182:185], v149
	ds_read_b128 v[186:189], v149 offset:1024
	ds_read_b128 v[190:193], v149 offset:2048
	ds_read_b128 v[194:197], v149 offset:3072
	ds_read_b128 v[198:201], v149 offset:4096
	ds_read_b128 v[202:205], v149 offset:5120
	ds_read_b128 v[206:209], v149 offset:6144
	ds_read_b128 v[210:213], v149 offset:7168
	global_load_lds_dwordx4 v[214:215], off
	v_lshl_add_u64 v[214:215], s[36:37], 0, v[138:139]
	s_add_i32 m0, s35, 0xe000
	s_nop 0
	global_load_lds_dwordx4 v[214:215], off
	s_waitcnt vmcnt(9)
	s_waitcnt lgkmcnt(0)
	s_barrier
	s_setprio 1
	s_waitcnt lgkmcnt(0)
	v_mfma_f32_16x16x32_bf16 v[124:127], v[150:153], v[182:185], v[124:127]
	v_mfma_f32_16x16x32_bf16 v[120:123], v[158:161], v[182:185], v[120:123]
	v_mfma_f32_16x16x32_bf16 v[108:111], v[150:153], v[190:193], v[108:111]
	v_mfma_f32_16x16x32_bf16 v[104:107], v[158:161], v[190:193], v[104:107]
	v_mfma_f32_16x16x32_bf16 v[92:95], v[150:153], v[198:201], v[92:95]
	v_mfma_f32_16x16x32_bf16 v[88:91], v[158:161], v[198:201], v[88:91]
	v_mfma_f32_16x16x32_bf16 v[76:79], v[150:153], v[206:209], v[76:79]
	v_mfma_f32_16x16x32_bf16 v[72:75], v[158:161], v[206:209], v[72:75]
	v_mfma_f32_16x16x32_bf16 v[124:127], v[154:157], v[186:189], v[124:127]
	v_mfma_f32_16x16x32_bf16 v[120:123], v[162:165], v[186:189], v[120:123]
	v_mfma_f32_16x16x32_bf16 v[108:111], v[154:157], v[194:197], v[108:111]
	v_mfma_f32_16x16x32_bf16 v[104:107], v[162:165], v[194:197], v[104:107]
	v_mfma_f32_16x16x32_bf16 v[92:95], v[154:157], v[202:205], v[92:95]
	v_mfma_f32_16x16x32_bf16 v[88:91], v[162:165], v[202:205], v[88:91]
	v_mfma_f32_16x16x32_bf16 v[76:79], v[154:157], v[210:213], v[76:79]
	v_mfma_f32_16x16x32_bf16 v[72:75], v[162:165], v[210:213], v[72:75]
	s_setprio 0
	s_setprio 1
	v_mfma_f32_16x16x32_bf16 v[116:119], v[166:169], v[182:185], v[116:119]
	v_mfma_f32_16x16x32_bf16 v[112:115], v[174:177], v[182:185], v[112:115]
	v_mfma_f32_16x16x32_bf16 v[100:103], v[166:169], v[190:193], v[100:103]
	v_mfma_f32_16x16x32_bf16 v[96:99], v[174:177], v[190:193], v[96:99]
	v_mfma_f32_16x16x32_bf16 v[84:87], v[166:169], v[198:201], v[84:87]
	v_mfma_f32_16x16x32_bf16 v[80:83], v[174:177], v[198:201], v[80:83]
	v_mfma_f32_16x16x32_bf16 v[68:71], v[166:169], v[206:209], v[68:71]
	v_mfma_f32_16x16x32_bf16 v[64:67], v[174:177], v[206:209], v[64:67]
	v_mfma_f32_16x16x32_bf16 v[116:119], v[170:173], v[186:189], v[116:119]
	v_mfma_f32_16x16x32_bf16 v[112:115], v[178:181], v[186:189], v[112:115]
	v_mfma_f32_16x16x32_bf16 v[100:103], v[170:173], v[194:197], v[100:103]
	v_mfma_f32_16x16x32_bf16 v[96:99], v[178:181], v[194:197], v[96:99]
	v_mfma_f32_16x16x32_bf16 v[84:87], v[170:173], v[202:205], v[84:87]
	v_mfma_f32_16x16x32_bf16 v[80:83], v[178:181], v[202:205], v[80:83]
	v_mfma_f32_16x16x32_bf16 v[68:71], v[170:173], v[210:213], v[68:71]
	v_mfma_f32_16x16x32_bf16 v[64:67], v[178:181], v[210:213], v[64:67]
	s_setprio 0
	s_barrier
	s_add_i32 s62, s50, s3
	v_lshl_add_u64 v[214:215], s[38:39], 0, v[130:131]
	s_mov_b32 m0, s62
	ds_read_b128 v[182:185], v149 offset:16384
	ds_read_b128 v[186:189], v149 offset:17408
	ds_read_b128 v[190:193], v149 offset:18432
	ds_read_b128 v[194:197], v149 offset:19456
	ds_read_b128 v[198:201], v149 offset:20480
	ds_read_b128 v[202:205], v149 offset:21504
	ds_read_b128 v[206:209], v149 offset:22528
	ds_read_b128 v[210:213], v149 offset:23552
	global_load_lds_dwordx4 v[214:215], off
	s_add_i32 m0, s62, 0x2000
	s_add_u32 s62, s38, 0x40000
	v_lshl_add_u64 v[216:217], s[38:39], 0, v[134:135]
	s_addc_u32 s63, s39, 0
	s_add_i32 s64, s51, s3
	global_load_lds_dwordx4 v[216:217], off
	v_lshl_add_u64 v[218:219], s[62:63], 0, v[130:131]
	s_mov_b32 m0, s64
	v_lshl_add_u64 v[222:223], s[40:41], 0, v[132:133]
	global_load_lds_dwordx4 v[218:219], off
	v_lshl_add_u64 v[218:219], s[62:63], 0, v[134:135]
	s_add_i32 m0, s64, 0x2000
	s_nop 0
	global_load_lds_dwordx4 v[218:219], off
	v_lshl_add_u64 v[218:219], s[40:41], 0, v[128:129]
	s_mov_b32 m0, s35
	s_nop 0
	global_load_lds_dwordx4 v[218:219], off
	s_mov_b32 m0, s42
	s_nop 0
	global_load_lds_dwordx4 v[222:223], off
	s_waitcnt vmcnt(9)
	s_waitcnt lgkmcnt(0)
	s_barrier
	s_setprio 1
	s_waitcnt lgkmcnt(0)
	v_mfma_f32_16x16x32_bf16 v[60:63], v[150:153], v[182:185], v[60:63]
	v_mfma_f32_16x16x32_bf16 v[56:59], v[158:161], v[182:185], v[56:59]
	v_mfma_f32_16x16x32_bf16 v[44:47], v[150:153], v[190:193], v[44:47]
	v_mfma_f32_16x16x32_bf16 v[40:43], v[158:161], v[190:193], v[40:43]
	v_mfma_f32_16x16x32_bf16 v[28:31], v[150:153], v[198:201], v[28:31]
	v_mfma_f32_16x16x32_bf16 v[24:27], v[158:161], v[198:201], v[24:27]
	v_mfma_f32_16x16x32_bf16 v[12:15], v[150:153], v[206:209], v[12:15]
	v_mfma_f32_16x16x32_bf16 v[8:11], v[158:161], v[206:209], v[8:11]
	v_mfma_f32_16x16x32_bf16 v[60:63], v[154:157], v[186:189], v[60:63]
	v_mfma_f32_16x16x32_bf16 v[56:59], v[162:165], v[186:189], v[56:59]
	v_mfma_f32_16x16x32_bf16 v[44:47], v[154:157], v[194:197], v[44:47]
	v_mfma_f32_16x16x32_bf16 v[40:43], v[162:165], v[194:197], v[40:43]
	v_mfma_f32_16x16x32_bf16 v[28:31], v[154:157], v[202:205], v[28:31]
	v_mfma_f32_16x16x32_bf16 v[24:27], v[162:165], v[202:205], v[24:27]
	v_mfma_f32_16x16x32_bf16 v[12:15], v[154:157], v[210:213], v[12:15]
	v_mfma_f32_16x16x32_bf16 v[8:11], v[162:165], v[210:213], v[8:11]
	s_setprio 0
	s_setprio 1
	v_mfma_f32_16x16x32_bf16 v[52:55], v[166:169], v[182:185], v[52:55]
	v_mfma_f32_16x16x32_bf16 v[48:51], v[174:177], v[182:185], v[48:51]
	v_mfma_f32_16x16x32_bf16 v[36:39], v[166:169], v[190:193], v[36:39]
	v_mfma_f32_16x16x32_bf16 v[32:35], v[174:177], v[190:193], v[32:35]
	v_mfma_f32_16x16x32_bf16 v[20:23], v[166:169], v[198:201], v[20:23]
	v_mfma_f32_16x16x32_bf16 v[16:19], v[174:177], v[198:201], v[16:19]
	v_mfma_f32_16x16x32_bf16 v[4:7], v[166:169], v[206:209], v[4:7]
	v_mfma_f32_16x16x32_bf16 v[0:3], v[174:177], v[206:209], v[0:3]
	v_mfma_f32_16x16x32_bf16 v[52:55], v[170:173], v[186:189], v[52:55]
	v_mfma_f32_16x16x32_bf16 v[48:51], v[178:181], v[186:189], v[48:51]
	v_mfma_f32_16x16x32_bf16 v[36:39], v[170:173], v[194:197], v[36:39]
	v_mfma_f32_16x16x32_bf16 v[32:35], v[178:181], v[194:197], v[32:35]
	v_mfma_f32_16x16x32_bf16 v[20:23], v[170:173], v[202:205], v[20:23]
	v_mfma_f32_16x16x32_bf16 v[16:19], v[178:181], v[202:205], v[16:19]
	v_mfma_f32_16x16x32_bf16 v[4:7], v[170:173], v[210:213], v[4:7]
	v_mfma_f32_16x16x32_bf16 v[0:3], v[178:181], v[210:213], v[0:3]
	s_setprio 0
	s_barrier
	s_add_i32 s62, 0, 0x18000
	s_add_i32 s63, 0, 0x1c000
	v_add_u32_e32 v162, s62, v145
	v_add_u32_e32 v178, s63, v145
	ds_read_b128 v[150:153], v162
	ds_read_b128 v[154:157], v162 offset:1024
	ds_read_b128 v[158:161], v162 offset:2048
	ds_read_b128 v[162:165], v162 offset:3072
	ds_read_b128 v[166:169], v178
	ds_read_b128 v[170:173], v178 offset:1024
	ds_read_b128 v[174:177], v178 offset:2048
	ds_read_b128 v[178:181], v178 offset:3072
	s_add_u32 s40, s40, 0x40000
	s_addc_u32 s41, s41, 0
	s_mov_b32 m0, s43
	v_lshl_add_u64 v[224:225], s[40:41], 0, v[128:129]
	ds_read_b128 v[182:185], v149 offset:32768
	ds_read_b128 v[186:189], v149 offset:33792
	ds_read_b128 v[190:193], v149 offset:34816
	ds_read_b128 v[194:197], v149 offset:35840
	ds_read_b128 v[198:201], v149 offset:36864
	ds_read_b128 v[202:205], v149 offset:37888
	ds_read_b128 v[206:209], v149 offset:38912
	ds_read_b128 v[210:213], v149 offset:39936
	global_load_lds_dwordx4 v[224:225], off
	v_lshl_add_u64 v[224:225], s[40:41], 0, v[132:133]
	s_mov_b32 m0, s44
	s_nop 0
	global_load_lds_dwordx4 v[224:225], off
	s_waitcnt vmcnt(8)
	s_waitcnt lgkmcnt(0)
	s_barrier
	s_setprio 1
	s_waitcnt lgkmcnt(0)
	v_mfma_f32_16x16x32_bf16 v[124:127], v[150:153], v[182:185], v[124:127]
	v_mfma_f32_16x16x32_bf16 v[120:123], v[158:161], v[182:185], v[120:123]
	v_mfma_f32_16x16x32_bf16 v[108:111], v[150:153], v[190:193], v[108:111]
	v_mfma_f32_16x16x32_bf16 v[104:107], v[158:161], v[190:193], v[104:107]
	v_mfma_f32_16x16x32_bf16 v[92:95], v[150:153], v[198:201], v[92:95]
	v_mfma_f32_16x16x32_bf16 v[88:91], v[158:161], v[198:201], v[88:91]
	v_mfma_f32_16x16x32_bf16 v[76:79], v[150:153], v[206:209], v[76:79]
	v_mfma_f32_16x16x32_bf16 v[72:75], v[158:161], v[206:209], v[72:75]
	v_mfma_f32_16x16x32_bf16 v[124:127], v[154:157], v[186:189], v[124:127]
	v_mfma_f32_16x16x32_bf16 v[120:123], v[162:165], v[186:189], v[120:123]
	v_mfma_f32_16x16x32_bf16 v[108:111], v[154:157], v[194:197], v[108:111]
	v_mfma_f32_16x16x32_bf16 v[104:107], v[162:165], v[194:197], v[104:107]
	v_mfma_f32_16x16x32_bf16 v[92:95], v[154:157], v[202:205], v[92:95]
	v_mfma_f32_16x16x32_bf16 v[88:91], v[162:165], v[202:205], v[88:91]
	v_mfma_f32_16x16x32_bf16 v[76:79], v[154:157], v[210:213], v[76:79]
	v_mfma_f32_16x16x32_bf16 v[72:75], v[162:165], v[210:213], v[72:75]
	s_setprio 0
	s_setprio 1
	v_mfma_f32_16x16x32_bf16 v[116:119], v[166:169], v[182:185], v[116:119]
	v_mfma_f32_16x16x32_bf16 v[112:115], v[174:177], v[182:185], v[112:115]
	v_mfma_f32_16x16x32_bf16 v[100:103], v[166:169], v[190:193], v[100:103]
	v_mfma_f32_16x16x32_bf16 v[96:99], v[174:177], v[190:193], v[96:99]
	v_mfma_f32_16x16x32_bf16 v[84:87], v[166:169], v[198:201], v[84:87]
	v_mfma_f32_16x16x32_bf16 v[80:83], v[174:177], v[198:201], v[80:83]
	v_mfma_f32_16x16x32_bf16 v[68:71], v[166:169], v[206:209], v[68:71]
	v_mfma_f32_16x16x32_bf16 v[64:67], v[174:177], v[206:209], v[64:67]
	v_mfma_f32_16x16x32_bf16 v[116:119], v[170:173], v[186:189], v[116:119]
	v_mfma_f32_16x16x32_bf16 v[112:115], v[178:181], v[186:189], v[112:115]
	v_mfma_f32_16x16x32_bf16 v[100:103], v[170:173], v[194:197], v[100:103]
	v_mfma_f32_16x16x32_bf16 v[96:99], v[178:181], v[194:197], v[96:99]
	v_mfma_f32_16x16x32_bf16 v[84:87], v[170:173], v[202:205], v[84:87]
	v_mfma_f32_16x16x32_bf16 v[80:83], v[178:181], v[202:205], v[80:83]
	v_mfma_f32_16x16x32_bf16 v[68:71], v[170:173], v[210:213], v[68:71]
	v_mfma_f32_16x16x32_bf16 v[64:67], v[178:181], v[210:213], v[64:67]
	s_setprio 0
	s_barrier
	s_add_i32 s40, s62, s3
	v_lshl_add_u64 v[214:215], v[214:215], 0, s[12:13]
	s_mov_b32 m0, s40
	ds_read_b128 v[182:185], v149 offset:49152
	ds_read_b128 v[186:189], v149 offset:50176
	ds_read_b128 v[190:193], v149 offset:51200
	ds_read_b128 v[194:197], v149 offset:52224
	ds_read_b128 v[198:201], v149 offset:53248
	ds_read_b128 v[202:205], v149 offset:54272
	ds_read_b128 v[206:209], v149 offset:55296
	ds_read_b128 v[210:213], v149 offset:56320
	global_load_lds_dwordx4 v[214:215], off
	s_add_i32 m0, s40, 0x2000
	s_add_u32 s38, s38, 0x40080
	v_lshl_add_u64 v[214:215], v[216:217], 0, s[12:13]
	s_addc_u32 s39, s39, 0
	s_add_i32 s40, s63, s3
	global_load_lds_dwordx4 v[214:215], off
	v_lshl_add_u64 v[214:215], s[38:39], 0, v[130:131]
	s_mov_b32 m0, s40
	s_nop 0
	global_load_lds_dwordx4 v[214:215], off
	v_lshl_add_u64 v[214:215], s[38:39], 0, v[134:135]
	s_add_i32 m0, s40, 0x2000
	s_nop 0
	global_load_lds_dwordx4 v[214:215], off
	v_lshl_add_u64 v[214:215], v[218:219], 0, s[12:13]
	s_mov_b32 m0, s47
	s_nop 0
	global_load_lds_dwordx4 v[214:215], off
	v_lshl_add_u64 v[214:215], v[222:223], 0, s[12:13]
	s_mov_b32 m0, s48
	s_nop 0
	global_load_lds_dwordx4 v[214:215], off
	s_waitcnt vmcnt(8)
	s_waitcnt lgkmcnt(0)
	s_barrier
	s_setprio 1
	s_waitcnt lgkmcnt(0)
	v_mfma_f32_16x16x32_bf16 v[60:63], v[150:153], v[182:185], v[60:63]
	v_mfma_f32_16x16x32_bf16 v[56:59], v[158:161], v[182:185], v[56:59]
	v_mfma_f32_16x16x32_bf16 v[44:47], v[150:153], v[190:193], v[44:47]
	v_mfma_f32_16x16x32_bf16 v[40:43], v[158:161], v[190:193], v[40:43]
	v_mfma_f32_16x16x32_bf16 v[28:31], v[150:153], v[198:201], v[28:31]
	v_mfma_f32_16x16x32_bf16 v[24:27], v[158:161], v[198:201], v[24:27]
	v_mfma_f32_16x16x32_bf16 v[12:15], v[150:153], v[206:209], v[12:15]
	v_mfma_f32_16x16x32_bf16 v[8:11], v[158:161], v[206:209], v[8:11]
	v_mfma_f32_16x16x32_bf16 v[60:63], v[154:157], v[186:189], v[60:63]
	v_mfma_f32_16x16x32_bf16 v[56:59], v[162:165], v[186:189], v[56:59]
	v_mfma_f32_16x16x32_bf16 v[44:47], v[154:157], v[194:197], v[44:47]
	v_mfma_f32_16x16x32_bf16 v[40:43], v[162:165], v[194:197], v[40:43]
	v_mfma_f32_16x16x32_bf16 v[28:31], v[154:157], v[202:205], v[28:31]
	v_mfma_f32_16x16x32_bf16 v[24:27], v[162:165], v[202:205], v[24:27]
	v_mfma_f32_16x16x32_bf16 v[12:15], v[154:157], v[210:213], v[12:15]
	v_mfma_f32_16x16x32_bf16 v[8:11], v[162:165], v[210:213], v[8:11]
	s_setprio 0
	s_setprio 1
	v_mfma_f32_16x16x32_bf16 v[52:55], v[166:169], v[182:185], v[52:55]
	v_mfma_f32_16x16x32_bf16 v[48:51], v[174:177], v[182:185], v[48:51]
	v_mfma_f32_16x16x32_bf16 v[36:39], v[166:169], v[190:193], v[36:39]
	v_mfma_f32_16x16x32_bf16 v[32:35], v[174:177], v[190:193], v[32:35]
	v_mfma_f32_16x16x32_bf16 v[20:23], v[166:169], v[198:201], v[20:23]
	v_mfma_f32_16x16x32_bf16 v[16:19], v[174:177], v[198:201], v[16:19]
	v_mfma_f32_16x16x32_bf16 v[4:7], v[166:169], v[206:209], v[4:7]
	v_mfma_f32_16x16x32_bf16 v[0:3], v[174:177], v[206:209], v[0:3]
	v_mfma_f32_16x16x32_bf16 v[52:55], v[170:173], v[186:189], v[52:55]
	v_mfma_f32_16x16x32_bf16 v[48:51], v[178:181], v[186:189], v[48:51]
	v_mfma_f32_16x16x32_bf16 v[36:39], v[170:173], v[194:197], v[36:39]
	v_mfma_f32_16x16x32_bf16 v[32:35], v[178:181], v[194:197], v[32:35]
	v_mfma_f32_16x16x32_bf16 v[20:23], v[170:173], v[202:205], v[20:23]
	v_mfma_f32_16x16x32_bf16 v[16:19], v[178:181], v[202:205], v[16:19]
	v_mfma_f32_16x16x32_bf16 v[4:7], v[170:173], v[210:213], v[4:7]
	v_mfma_f32_16x16x32_bf16 v[0:3], v[178:181], v[210:213], v[0:3]
	s_setprio 0
	s_barrier
	s_add_i32 s61, s61, 2
	s_add_u32 s36, s36, 0x100
	s_addc_u32 s37, s37, 0
	s_add_u32 s59, s59, 0x100
	s_addc_u32 s60, s60, 0
	s_cmp_eq_u32 s100, 0
	s_cbranch_scc1 .Ldhs8_bidle
	s_cmp_eq_u32 s61, 0
	s_cbranch_scc1 .Ldhs8_e1
	s_cmp_eq_u32 s61, 2
	s_cbranch_scc1 .Ldhs8_e2
	s_cmp_eq_u32 s61, 4
	s_cbranch_scc1 .Ldhs8_e3
	s_cmp_eq_u32 s61, 6
	s_cbranch_scc1 .Ldhs8_e4
	s_cmp_eq_u32 s61, 8
	s_cbranch_scc1 .Ldhs8_e5
	s_cmp_eq_u32 s61, 10
	s_cbranch_scc1 .Ldhs8_e6
	s_cmp_eq_u32 s61, 12
	s_cbranch_scc1 .Ldhs8_e7
.Ldhs8_exit:
	s_and_b64 vcc, exec, s[14:15]
	s_cbranch_vccz .LBB0_880
	s_barrier

.Ldhs8_bidle:
	s_cmp_gt_u32 s61, 13
	s_cbranch_scc1 .Ldhs8_exit
	global_load_ubyte v255, v221, s[16:17]
	s_branch .Ldhs8_body
